# A+B plus SB units remapped so one XCD sweeps a head (shared KV tiles hit L2), 7-tile KV window
# speedup vs baseline: 1.0081x; 1.0065x over previous
; #define LAS __attribute__((address_space(3)))
; DI void sb_wg_unit(bf16_t* act, int b, int hh, int Qb, LAS unsigned char* lds, volatile LAS unsigned* ctl, int tid, int wid, int lane) {
;     const int r = lane & 31, h = lane >> 5;
;     const int Q = Qb * 256, q0 = Q + 32 * wid, qpos = q0 + r;
;     const size_t rowq = (size_t)b * SEQ + qpos;
;     bf16x8 qf[4]; load_q(qf, act + rowq * PITCH + C_QA + hh * 64, h);
;     f32x16 o0, o1;
; #pragma unroll
;     for (int i = 0; i < 16; ++i) { o0[i] = 0.f; o1[i] = 0.f; }
;     float C = 1.f;
;     const bf16_t* kgb = act + (size_t)b * SEQ * PITCH + C_KA + hh * 64;
;     int t = q0 >> 6;
;     bool done = false;
;     int t_top = (Q >> 6) + 3;
; #pragma unroll 1
;     for (;;) {
;         const int t_bot = (t_top - 7) > 0 ? (t_top - 7) : 0, nt = t_top - t_bot + 1;
;         __syncthreads();
;         if (tid == 0) ctl[7] = 0u;
;         coop_load_tiles(kgb, C_VA - C_KA, t_top, nt, lds, wid, lane);
;         __syncthreads();
; __global__ void __launch_bounds__(512, 2) hybrid_fwd(Params p) {
;     ...
;             for (int u = wg; u < 1024; u += G) {
;                 const int Qb = u & 31, hh = (u >> 5) & 7, b = u >> 8;
;                 sb_wg_unit(act, b, hh, Qb, lds, ctl, tid, wid, lane);
.LBB0_334:
	s_and_b32 s98, s17, 7
	s_lshl_b32 s98, s98, 5
	s_bfe_u32 s99, s17, 0x50003
	s_or_b32 s98, s98, s99
	s_andn2_b32 s99, s17, 0xff
	s_or_b32 s98, s98, s99
	s_and_b32 s10, s98, 31
	s_lshl_b32 s21, s10, 8
	s_ashr_i32 s6, s98, 8
	s_add_i32 s21, s21, s16
	v_or_b32_e32 v86, s21, v83
	s_ashr_i32 s7, s6, 31
	s_lshl_b64 s[8:9], s[6:7], 13
	v_ashrrev_i32_e32 v87, 31, v86
	v_lshl_add_u64 v[2:3], s[8:9], 0, v[86:87]
	v_mov_b64_e32 v[4:5], s[76:77]
	v_mad_u64_u32 v[4:5], s[8:9], v2, s31, v[4:5]
	s_lshl_b32 s7, s98, 2
	v_mad_i32_i24 v5, v3, s31, v5
	s_and_b32 s38, s7, 0x380
	v_lshl_add_u64 v[88:89], v[4:5], 0, s[38:39]
	v_lshl_add_u64 v[84:85], v[88:89], 0, v[0:1]
	global_load_dwordx4 v[66:69], v[84:85], off
	global_load_dwordx4 v[70:73], v[84:85], off offset:32
	global_load_dwordx4 v[74:77], v[84:85], off offset:64
	global_load_dwordx4 v[78:81], v[84:85], off offset:96
	s_mul_hi_i32 s7, s6, 0x6400000
	s_mul_i32 s6, s6, 0x6400000
	s_add_u32 s6, s76, s6
	s_addc_u32 s7, s77, s7
	s_add_u32 s6, s6, s38
	s_addc_u32 s7, s7, 0
	s_lshl_b32 s8, s10, 2
	s_ashr_i32 s24, s21, 6
	s_or_b32 s25, s8, 3
	v_mov_b32_e32 v18, v1
	v_mov_b32_e32 v19, v1
	s_add_u32 s6, s6, s46
	v_mov_b32_e32 v20, v1
	v_mov_b32_e32 v21, v1
	v_mov_b32_e32 v22, v1
	v_mov_b32_e32 v23, v1
	v_mov_b32_e32 v24, v1
	v_mov_b32_e32 v25, v1
	v_mov_b32_e32 v26, v1
	v_mov_b32_e32 v27, v1
	v_mov_b32_e32 v28, v1
	v_mov_b32_e32 v29, v1
	v_mov_b32_e32 v30, v1
	v_mov_b32_e32 v31, v1
	v_mov_b32_e32 v32, v1
	v_mov_b32_e32 v33, v1
	s_waitcnt lgkmcnt(0)
	v_mov_b64_e32 v[2:3], v[18:19]
	s_addc_u32 s7, s7, s47
	v_mov_b32_e32 v91, 1.0
	s_mov_b64 s[8:9], 0
	v_mov_b64_e32 v[4:5], v[20:21]
	v_mov_b64_e32 v[6:7], v[22:23]
	v_mov_b64_e32 v[8:9], v[24:25]
	v_mov_b64_e32 v[10:11], v[26:27]
	v_mov_b64_e32 v[12:13], v[28:29]
	v_mov_b64_e32 v[14:15], v[30:31]
	v_mov_b64_e32 v[16:17], v[32:33]
	s_branch .LBB0_336
.LBB0_335:
	s_or_b64 exec, exec, s[10:11]
	v_mov_b32_e32 v34, s5
	s_waitcnt lgkmcnt(0)
	s_barrier
	ds_read_b32 v34, v34
	s_add_i32 s25, s22, -7
	s_waitcnt lgkmcnt(0)
	v_cmp_ne_u32_e32 vcc, 0, v34
	s_cbranch_vccz .LBB0_333
.LBB0_336:
	s_barrier
	s_and_saveexec_b64 s[10:11], s[40:41]
	v_mov_b32_e32 v34, s5
	ds_write_b32 v34, v1
	s_or_b64 exec, exec, s[10:11]
	s_max_i32 s22, s25, 6
	s_add_i32 s23, s22, -6
	s_sub_i32 s26, s25, s23
	s_cmp_lt_i32 s26, 0
	s_cbranch_scc1 .LBB0_353
	v_lshl_add_u32 v87, s25, 6, v94
	s_mov_b32 s12, 0
	v_mov_b32_e32 v34, 0
	v_mov_b32_e32 v35, 0
	v_mov_b32_e32 v36, 0
	v_mov_b32_e32 v37, 0
	v_mov_b32_e32 v38, 0
	v_mov_b32_e32 v39, 0
	v_mov_b32_e32 v40, 0
	v_mov_b32_e32 v41, 0
	s_waitcnt vmcnt(1)
	v_mov_b32_e32 v42, 0
	v_mov_b32_e32 v43, 0
	v_mov_b32_e32 v44, 0
	v_mov_b32_e32 v45, 0
	v_mov_b32_e32 v46, 0
	v_mov_b32_e32 v47, 0
	v_mov_b32_e32 v48, 0
	v_mov_b32_e32 v49, 0
	v_mov_b32_e32 v50, 0
	v_mov_b32_e32 v51, 0
	v_mov_b32_e32 v52, 0
	v_mov_b32_e32 v53, 0
	s_waitcnt vmcnt(0)
	v_mov_b32_e32 v54, 0
	v_mov_b32_e32 v55, 0
	v_mov_b32_e32 v56, 0
	v_mov_b32_e32 v57, 0
	v_mov_b32_e32 v90, v93
	v_mov_b32_e32 v97, v92
	s_branch .LBB0_341

; __global__ void __launch_bounds__(512, 2) hybrid_fwd(Params p) {
	.amdhsa_kernel _Z10hybrid_fwd6Params
		.amdhsa_group_segment_fixed_size 0
		.amdhsa_private_segment_fixed_size 0
		.amdhsa_kernarg_size 352
		.amdhsa_user_sgpr_count 2
		.amdhsa_user_sgpr_dispatch_ptr 0
		.amdhsa_user_sgpr_queue_ptr 0
		.amdhsa_user_sgpr_kernarg_segment_ptr 1
		.amdhsa_user_sgpr_dispatch_id 0
		.amdhsa_user_sgpr_kernarg_preload_length 0
		.amdhsa_user_sgpr_kernarg_preload_offset 0
		.amdhsa_user_sgpr_private_segment_size 0
		.amdhsa_uses_dynamic_stack 0
		.amdhsa_enable_private_segment 0
		.amdhsa_system_sgpr_workgroup_id_x 1
		.amdhsa_system_sgpr_workgroup_id_y 0
		.amdhsa_system_sgpr_workgroup_id_z 0
		.amdhsa_system_sgpr_workgroup_info 0
		.amdhsa_system_vgpr_workitem_id 2
		.amdhsa_next_free_vgpr 256
		.amdhsa_next_free_sgpr 102
		.amdhsa_accum_offset 256
		.amdhsa_reserve_vcc 1
		.amdhsa_float_round_mode_32 0
		.amdhsa_float_round_mode_16_64 0
		.amdhsa_float_denorm_mode_32 3
		.amdhsa_float_denorm_mode_16_64 3
		.amdhsa_dx10_clamp 1
		.amdhsa_ieee_mode 1
		.amdhsa_fp16_overflow 0
		.amdhsa_tg_split 0
		.amdhsa_exception_fp_ieee_invalid_op 0
		.amdhsa_exception_fp_denorm_src 0
		.amdhsa_exception_fp_ieee_div_zero 0
		.amdhsa_exception_fp_ieee_overflow 0
		.amdhsa_exception_fp_ieee_underflow 0
		.amdhsa_exception_fp_ieee_inexact 0
		.amdhsa_exception_int_div_zero 0
	.end_amdhsa_kernel

; __global__ void __launch_bounds__(512, 2) hybrid_fwd(Params p) {
amdhsa.kernels:
  - .agpr_count:     0
    .args:
      - .offset:         0
        .size:           96
        .value_kind:     by_value
      - .offset:         96
        .size:           4
        .value_kind:     hidden_block_count_x
      - .offset:         100
        .size:           4
        .value_kind:     hidden_block_count_y
      - .offset:         104
        .size:           4
        .value_kind:     hidden_block_count_z
      - .offset:         108
        .size:           2
        .value_kind:     hidden_group_size_x
      - .offset:         110
        .size:           2
        .value_kind:     hidden_group_size_y
      - .offset:         112
        .size:           2
        .value_kind:     hidden_group_size_z
      - .offset:         114
        .size:           2
        .value_kind:     hidden_remainder_x
      - .offset:         116
        .size:           2
        .value_kind:     hidden_remainder_y
      - .offset:         118
        .size:           2
        .value_kind:     hidden_remainder_z
      - .offset:         136
        .size:           8
        .value_kind:     hidden_global_offset_x
      - .offset:         144
        .size:           8
        .value_kind:     hidden_global_offset_y
      - .offset:         152
        .size:           8
        .value_kind:     hidden_global_offset_z
      - .offset:         160
        .size:           2
        .value_kind:     hidden_grid_dims
      - .offset:         184
        .size:           8
        .value_kind:     hidden_multigrid_sync_arg
      - .offset:         216
        .size:           4
        .value_kind:     hidden_dynamic_lds_size
    .group_segment_fixed_size: 0
    .kernarg_segment_align: 8
    .kernarg_segment_size: 352
    .language:       OpenCL C
    .language_version:
      - 2
      - 0
    .max_flat_workgroup_size: 512
    .name:           _Z10hybrid_fwd6Params
    .private_segment_fixed_size: 0
    .sgpr_count:     108
    .sgpr_spill_count: 140
    .symbol:         _Z10hybrid_fwd6Params.kd
    .uniform_work_group_size: 1
    .uses_dynamic_stack: false
    .vgpr_count:     256
    .vgpr_spill_count: 0
    .wavefront_size: 64
